# final stack plus P9 work placement: the split-K slab sums of the MIX sample rows run on workgroups 128..191 (slack in P10) instead of 0..63 (which carry P10's sample pieces); same rows and arithmetic
# speedup vs baseline: 1.0078x; 1.0040x over previous
; #define GAS __attribute__((address_space(1)))
; __device__ __forceinline__ unsigned pk2(float lo, float hi) { return f2bf(lo) | (f2bf(hi) << 16); }
; __device__ __forceinline__ void mixfix_all(Frame& F, int nslab) {
;     const int gw = F.vcu * NWAVES + F.wave, NGW = F.G * NWAVES, lane = F.lane;
;     bf16* MIX = WSP(bf16, WS_MIX);
;     for (int r = gw; r < NS; r += NGW) {
;         const GAS f32x4* sp = (const GAS f32x4*)(WSP(float, WS_SLAB) + (size_t)r * D) + lane; f32x4 t[8];
; #pragma unroll
;         for (int j = 0; j < 8; ++j) t[j] = sp[64 * j];
;         _Pragma("unroll 1") for (int s = 1; s < nslab; ++s) { sp += (size_t)NS * D / 4;
; #pragma unroll
;             for (int j = 0; j < 8; ++j) t[j] += sp[64 * j]; }
; #pragma unroll
;         for (int j = 0; j < 8; ++j) { v2u w; w.x = pk2(t[j][0], t[j][1]); w.y = pk2(t[j][2], t[j][3]); ((GAS v2u*)(MIX + (size_t)(NP + r) * D))[lane + 64 * j] = w; }
;     }
; }
.LBB0_1302:
	s_cmp_lt_i32 s92, 10
	s_cselect_b64 s[6:7], -1, 0
	s_and_b64 s[8:9], s[6:7], s[0:1]
	s_andn2_b64 vcc, exec, s[8:9]
	s_cbranch_vccnz .LBB0_1331
	v_readlane_b32 s0, v245, 10
	s_lshl_b32 s0, s0, 3
	s_add_i32 s0, s0, s97
	s_cmpk_lg_i32 s96, 0x100
	s_cbranch_scc1 .Lmixrow_keep
	s_addk_i32 s0, 0xfc00
.Lmixrow_keep:
	v_mov_b32_e32 v144, v1
	s_cmpk_gt_u32 s0, 0x1ff
	v_readlane_b32 s1, v245, 11
	s_cbranch_scc1 .LBB0_1308
	v_and_b32_e32 v6, 63, v144
	v_lshlrev_b32_e32 v2, 4, v6
	v_mov_b32_e32 v3, 0
	v_lshl_add_u64 v[4:5], s[34:35], 0, v[2:3]
	s_mov_b64 s[10:11], 0x3ab00000
	v_lshl_add_u64 v[34:35], v[4:5], 0, s[10:11]
	v_lshlrev_b32_e32 v4, 3, v6
	v_mov_b32_e32 v5, v3
	v_lshl_add_u64 v[4:5], s[34:35], 0, v[4:5]
	s_mov_b64 s[10:11], 0x38900000
	s_ashr_i32 s1, s0, 31
	s_lshl_b32 s4, s96, 3
	v_lshl_add_u64 v[36:37], v[4:5], 0, s[10:11]
	s_lshl_b64 s[10:11], s[0:1], 13
	s_add_u32 s10, s34, s10
	s_addc_u32 s11, s35, s11
	s_ashr_i32 s5, s4, 31
	v_lshl_add_u64 v[38:39], s[10:11], 0, v[2:3]
	s_lshl_b64 s[10:11], s[4:5], 13
	s_mov_b32 s3, 0x3af00000
	s_mov_b32 s5, 0x3af01000
	s_movk_i32 s16, 0x7fff
	s_mov_b32 s17, 0xffff0000
	s_mov_b64 s[12:13], 0x2000000
	s_brev_b32 s18, 64
